# attention loop: map-1 waves prefetch V frags before the barrier and K frags under the PV MFMAs; dead s_nop pads removed; pure reschedule
# speedup vs baseline: 1.0088x; 1.0088x over previous
; #define MFMA32(a, b, c) __builtin_amdgcn_mfma_f32_32x32x16_bf16((a), (b), (c), 0, 0, 0)
; #define AT_LOAD(t) do { _Pragma("unroll") for (int i = 0; i < 2; ++i) { const int p = tid + 512 * i; \
;             kr[i] = *(const u32x4*)(kbase + (size_t)((t) * 64 + (p >> 4)) * HP1 + (p & 15) * 8); \
;             vr[i] = *(const u32x4*)(vbase + (size_t)(p >> 3) * R + (t) * 64 + (p & 7) * 8); } } while (0)
; #define AT_NOP() asm volatile("s_nop 7\n\ts_nop 7" ::: "memory")
; #define AT_RD4(d0, d1, d2, d3, addr, o0, o1, o2, o3) do { DSR(d0, addr, o0); DSR(d1, addr, o1); DSR(d2, addr, o2); DSR(d3, addr, o3); } while (0)
; #define AT_WAIT8(a0, a1, a2, a3, a4, a5, a6, a7) asm volatile("s_waitcnt lgkmcnt(0)" : "+v"(a0), "+v"(a1), "+v"(a2), "+v"(a3), "+v"(a4), "+v"(a5), "+v"(a6), "+v"(a7) :: "memory")
; #define AT_PVRD(addr) do { AT_RDG(vf[0], vf[1], vf[2], vf[3], addr, 0); AT_RDG(vf[4], vf[5], vf[6], vf[7], addr, 1); } while (0)
; __device__ __forceinline__ void attn_phase(KA a, lds8* lds, int tid, int lane, int wave) {
;     ...
;         for (int t = 0; t < nt; ++t) {
;             const int bnext = bcur == 2 * AT_BUF ? 0 : bcur + AT_BUF;
;             if (t + 1 < nt) AT_LOAD(t + 1);
;             if (map == 1 && t > 0) { AT_PVRD(vaddr0 + bprev); AT_PVMM(vaddr0 + bprev); AT_NOP(); }
;             AT_RD4(kf[0], kf[1], kf[2], kf[3], kaddr0 + bcur, 0, 32, 64, 96); AT_RD4(vf[0], vf[1], vf[2], vf[3], kaddr0 + bcur, 4608, 4640, 4672, 4704);
;             AT_WAIT8(kf[0], kf[1], kf[2], kf[3], vf[0], vf[1], vf[2], vf[3]);
;             f32x16 s0, s1;
; #pragma unroll
;             for (int ks = 0; ks < 4; ++ks) { s0 = MFMA32(kf[ks], qf[ks], ks == 0 ? negm : s0); s1 = MFMA32(vf[ks], qf[ks], ks == 0 ? negm : s1); }
;             if (map == 0) { AT_NOP(); AT_PVRD(vaddr0 + bcur); }
.LBB0_1304:
	s_add_i32 s61, s15, 1
	s_cmp_lt_u32 s61, s60
	s_cselect_b64 s[54:55], -1, 0
	s_cmp_ge_u32 s61, s60
	s_cbranch_scc1 .LBB0_1306
	v_lshl_add_u64 v[250:251], s[24:25], 0, v[214:215]
	v_lshl_add_u64 v[252:253], s[24:25], 0, v[218:219]
	global_load_dwordx4 v[144:147], v[250:251], off
	global_load_dwordx4 v[148:151], v[252:253], off
	v_lshl_add_u64 v[250:251], s[24:25], 0, v[212:213]
	v_lshl_add_u64 v[252:253], s[24:25], 0, v[216:217]
	global_load_dwordx4 v[152:155], v[250:251], off
	global_load_dwordx4 v[156:159], v[252:253], off
.LBB0_1306:
	s_cmp_eq_u32 s15, 0
	s_cselect_b64 s[8:9], -1, 0
	s_or_b64 s[8:9], s[30:31], s[8:9]
	s_and_b64 vcc, exec, s[8:9]
	s_cbranch_vccnz .LBB0_1308
	v_add_u32_e32 v168, s14, v232
	v_add_u32_e32 v249, s18, v244
	v_mfma_f32_32x32x16_bf16 v[48:63], v[96:99], v[88:91], v[48:63]
	v_mfma_f32_32x32x16_bf16 v[32:47], v[100:103], v[88:91], v[32:47]
	v_mfma_f32_32x32x16_bf16 v[16:31], v[104:107], v[88:91], v[16:31]
	v_mfma_f32_32x32x16_bf16 v[0:15], v[108:111], v[88:91], v[0:15]
	ds_read_b128 v[88:91], v168 offset:64
	ds_read_b128 v[96:99], v168 offset:0x1240
	ds_read_b128 v[100:103], v168 offset:0x2440
	ds_read_b128 v[104:107], v168 offset:0x3640
	ds_read_b128 v[108:111], v168 offset:0x60
	ds_read_b128 v[160:163], v168 offset:0x1260
	ds_read_b128 v[164:167], v168 offset:0x2460
	v_mfma_f32_32x32x16_bf16 v[48:63], v[112:115], v[92:95], v[48:63]
	v_mfma_f32_32x32x16_bf16 v[32:47], v[116:119], v[92:95], v[32:47]
	v_mfma_f32_32x32x16_bf16 v[16:31], v[120:123], v[92:95], v[16:31]
	v_mfma_f32_32x32x16_bf16 v[0:15], v[124:127], v[92:95], v[0:15]
	ds_read_b128 v[92:95], v168 offset:0x3660
	s_waitcnt lgkmcnt(0)
	ds_read_b128 v[112:115], v249 offset:0
	ds_read_b128 v[220:223], v249 offset:32
	ds_read_b128 v[224:227], v249 offset:64
	ds_read_b128 v[228:231], v249 offset:0x60
	ds_read_b128 v[116:119], v249 offset:0x1200
	ds_read_b128 v[120:123], v249 offset:0x1220
	ds_read_b128 v[168:171], v249 offset:0x1240
	ds_read_b128 v[172:175], v249 offset:0x1260
	v_mfma_f32_32x32x16_bf16 v[48:63], v[88:91], v[80:83], v[48:63]
	v_mfma_f32_32x32x16_bf16 v[32:47], v[96:99], v[80:83], v[32:47]
	v_mfma_f32_32x32x16_bf16 v[16:31], v[100:103], v[80:83], v[16:31]
	v_mfma_f32_32x32x16_bf16 v[0:15], v[104:107], v[80:83], v[0:15]
	v_mfma_f32_32x32x16_bf16 v[48:63], v[108:111], v[84:87], v[48:63]
	v_mfma_f32_32x32x16_bf16 v[32:47], v[160:163], v[84:87], v[32:47]
	v_mfma_f32_32x32x16_bf16 v[16:31], v[164:167], v[84:87], v[16:31]
	v_mfma_f32_32x32x16_bf16 v[0:15], v[92:95], v[84:87], v[0:15]
	s_branch .Lat_qk
.LBB0_1308:
	v_add_u32_e32 v84, s18, v244
	ds_read_b128 v[112:115], v84 offset:0
	ds_read_b128 v[220:223], v84 offset:32
	ds_read_b128 v[224:227], v84 offset:64
	ds_read_b128 v[228:231], v84 offset:0x60
	ds_read_b128 v[116:119], v84 offset:0x1200
	ds_read_b128 v[120:123], v84 offset:0x1220
	ds_read_b128 v[168:171], v84 offset:0x1240
	ds_read_b128 v[172:175], v84 offset:0x1260
.Lat_qk:
	v_cndmask_b32_e64 v176, 0, 1, s[20:21]
	s_waitcnt lgkmcnt(0)
	v_cmp_ne_u32_e64 s[12:13], 1, v176
	v_mfma_f32_32x32x16_bf16 v[96:111], v[112:115], v[128:131], v[64:79]
	s_andn2_b64 vcc, exec, s[20:21]
	v_add_u32_e32 v176, s18, v232
	v_mfma_f32_32x32x16_bf16 v[80:95], v[116:119], v[128:131], v[64:79]
	v_mfma_f32_32x32x16_bf16 v[96:111], v[220:223], v[132:135], v[96:111]
	v_mfma_f32_32x32x16_bf16 v[80:95], v[120:123], v[132:135], v[80:95]
	v_mfma_f32_32x32x16_bf16 v[96:111], v[224:227], v[136:139], v[96:111]
	v_mfma_f32_32x32x16_bf16 v[80:95], v[168:171], v[136:139], v[80:95]
	v_mfma_f32_32x32x16_bf16 v[96:111], v[228:231], v[140:143], v[96:111]
	v_mfma_f32_32x32x16_bf16 v[80:95], v[172:175], v[140:143], v[80:95]
	s_cbranch_vccnz .LBB0_1310
	ds_read_b128 v[160:163], v176 offset:0
	ds_read_b128 v[164:167], v176 offset:0x1200
	ds_read_b128 v[168:171], v176 offset:0x2400
	ds_read_b128 v[172:175], v176 offset:0x3600
	ds_read_b128 v[112:115], v176 offset:32
	ds_read_b128 v[116:119], v176 offset:0x1220
	ds_read_b128 v[120:123], v176 offset:0x2420
	ds_read_b128 v[124:127], v176 offset:0x3620

; __device__ __forceinline__ unsigned pk2(float lo, float hi) { return cvt_pk_bf16(lo, hi); }
; __device__ __forceinline__ float fadd_s(float a, float b) { float r; asm("v_add_f32_e32 %0, %1, %2" : "=v"(r) : "v"(a), "v"(b)); return r; }
; #define AT_STORE(bo) do { _Pragma("unroll") for (int i = 0; i < 2; ++i) { const int p = tid + 512 * i; const int part = p & 15; \
;             *(LAS u32x4*)(lds + (bo) + (part >> 3) * AT_K2 + (p >> 4) * AT_KS + (part & 7) * 16) = kr[i]; \
;             *(LAS u32x4*)(lds + (bo) + AT_V + (p >> 3) * AT_KS + (p & 7) * 16) = vr[i]; } } while (0)
; __device__ __forceinline__ void attn_phase(KA a, lds8* lds, int tid, int lane, int wave) {
;     ...
;             for (int r = 0; r < 16; r += 2) { lsA = fadd_s(lsA, s0[r]); lsB = fadd_s(lsB, s1[r]); lsC = fadd_s(lsC, s0[r + 1]); lsD = fadd_s(lsD, s1[r + 1]); }
; #pragma unroll
;             for (int s2 = 0; s2 < 2; ++s2) { u32x4 w0, w1;
;                 w0.x = pk2(s0[8 * s2], s0[8 * s2 + 1]); w0.y = pk2(s0[8 * s2 + 2], s0[8 * s2 + 3]); w0.z = pk2(s0[8 * s2 + 4], s0[8 * s2 + 5]); w0.w = pk2(s0[8 * s2 + 6], s0[8 * s2 + 7]);
;                 w1.x = pk2(s1[8 * s2], s1[8 * s2 + 1]); w1.y = pk2(s1[8 * s2 + 2], s1[8 * s2 + 3]); w1.z = pk2(s1[8 * s2 + 4], s1[8 * s2 + 5]); w1.w = pk2(s1[8 * s2 + 6], s1[8 * s2 + 7]);
;                 pf[0][s2] = __builtin_bit_cast(bf16x8, w0); pf[1][s2] = __builtin_bit_cast(bf16x8, w1); }
;             if (map == 0) AT_PVMM(vaddr0 + bcur);
;             if (t + 1 < nt) AT_STORE(bnext);
.LBB0_1312:
	v_add_f32_e32 v88, v211, v224
	s_nop 0
	v_add_f32_e32 v89, v210, v80
	v_add_f32_e32 v90, v209, v225
	v_add_f32_e32 v91, v208, v81
	s_and_b64 vcc, exec, s[12:13]
	v_add_f32_e32 v88, v88, v226
	v_add_f32_e32 v89, v89, v82
	v_add_f32_e32 v90, v90, v227
	v_add_f32_e32 v91, v91, v83
	s_nop 0
	v_add_f32_e32 v88, v88, v228
	v_add_f32_e32 v89, v89, v220
	v_add_f32_e32 v90, v90, v229
	v_add_f32_e32 v91, v91, v221
	s_nop 0
	v_add_f32_e32 v88, v88, v230
	v_add_f32_e32 v89, v89, v222
	v_add_f32_e32 v90, v90, v231
	v_add_f32_e32 v91, v91, v223
	s_nop 0
	v_add_f32_e32 v88, v88, v100
	v_add_f32_e32 v89, v89, v84
	v_add_f32_e32 v90, v90, v101
	v_add_f32_e32 v91, v91, v85
	s_nop 0
	v_add_f32_e32 v88, v88, v102
	v_add_f32_e32 v89, v89, v86
	v_add_f32_e32 v90, v90, v103
	v_add_f32_e32 v91, v91, v87
	s_nop 0
	v_add_f32_e32 v88, v88, v104
	v_add_f32_e32 v89, v89, v98
	v_add_f32_e32 v90, v90, v105
	v_add_f32_e32 v91, v91, v99
	s_nop 0
	v_add_f32_e32 v211, v88, v106
	v_add_f32_e32 v210, v89, v96
	v_add_f32_e32 v209, v90, v107
	v_add_f32_e32 v208, v91, v97
	v_cvt_pk_bf16_f32 v88, v224, v225
	v_cvt_pk_bf16_f32 v89, v226, v227
	v_cvt_pk_bf16_f32 v90, v228, v229
	v_cvt_pk_bf16_f32 v91, v230, v231
	v_cvt_pk_bf16_f32 v80, v80, v81
	v_cvt_pk_bf16_f32 v81, v82, v83
	v_cvt_pk_bf16_f32 v82, v220, v221
	v_cvt_pk_bf16_f32 v83, v222, v223
	v_cvt_pk_bf16_f32 v92, v100, v101
	v_cvt_pk_bf16_f32 v93, v102, v103
	v_cvt_pk_bf16_f32 v94, v104, v105
	v_cvt_pk_bf16_f32 v95, v106, v107
	v_cvt_pk_bf16_f32 v84, v84, v85
	v_cvt_pk_bf16_f32 v85, v86, v87
	v_cvt_pk_bf16_f32 v86, v98, v99
	v_cvt_pk_bf16_f32 v87, v96, v97
	s_cbranch_vccnz .Lat_m1_pvrd
	s_waitcnt lgkmcnt(0)
	ds_read_b128 v[96:99], v176 offset:64
	ds_read_b128 v[100:103], v176 offset:0x1240
	ds_read_b128 v[104:107], v176 offset:0x2440
	s_nop 0
	v_mfma_f32_32x32x16_bf16 v[48:63], v[160:163], v[88:91], v[48:63]
	ds_read_b128 v[160:163], v176 offset:0x3640
	v_mfma_f32_32x32x16_bf16 v[32:47], v[164:167], v[88:91], v[32:47]
	ds_read_b128 v[164:167], v176 offset:0x60
	v_mfma_f32_32x32x16_bf16 v[16:31], v[168:171], v[88:91], v[16:31]
	ds_read_b128 v[168:171], v176 offset:0x1260
	v_mfma_f32_32x32x16_bf16 v[0:15], v[172:175], v[88:91], v[0:15]
	ds_read_b128 v[172:175], v176 offset:0x2460
	ds_read_b128 v[220:223], v176 offset:0x3660
	v_mfma_f32_32x32x16_bf16 v[48:63], v[112:115], v[92:95], v[48:63]
	v_mfma_f32_32x32x16_bf16 v[32:47], v[116:119], v[92:95], v[32:47]
	v_mfma_f32_32x32x16_bf16 v[16:31], v[120:123], v[92:95], v[16:31]
	v_mfma_f32_32x32x16_bf16 v[0:15], v[124:127], v[92:95], v[0:15]
	s_waitcnt lgkmcnt(0)
	v_mfma_f32_32x32x16_bf16 v[48:63], v[96:99], v[80:83], v[48:63]
	v_mfma_f32_32x32x16_bf16 v[32:47], v[100:103], v[80:83], v[32:47]
	v_mfma_f32_32x32x16_bf16 v[16:31], v[104:107], v[80:83], v[16:31]
	v_mfma_f32_32x32x16_bf16 v[0:15], v[160:163], v[80:83], v[0:15]
	v_mfma_f32_32x32x16_bf16 v[48:63], v[164:167], v[84:87], v[48:63]
	v_mfma_f32_32x32x16_bf16 v[32:47], v[168:171], v[84:87], v[32:47]
	v_mfma_f32_32x32x16_bf16 v[16:31], v[172:175], v[84:87], v[16:31]
	v_mfma_f32_32x32x16_bf16 v[0:15], v[220:223], v[84:87], v[0:15]
	s_branch .LBB0_1314
.Lat_m1_pvrd:
	ds_read_b128 v[96:99], v176 offset:0
	ds_read_b128 v[100:103], v176 offset:0x1200
	ds_read_b128 v[104:107], v176 offset:0x2400
	ds_read_b128 v[108:111], v176 offset:0x3600
	ds_read_b128 v[112:115], v176 offset:32
	ds_read_b128 v[116:119], v176 offset:0x1220
	ds_read_b128 v[120:123], v176 offset:0x2420
	ds_read_b128 v[124:127], v176 offset:0x3620
.LBB0_1314:
	s_add_i32 s8, s18, 0x9000
	s_cmp_lg_u32 s18, 0x12000
	s_cselect_b32 s62, s8, 0
	s_andn2_b64 vcc, exec, s[54:55]
	s_cbranch_vccnz .LBB0_1316
	s_add_i32 s8, s62, 0
	v_add_u32_e32 v250, s8, v234
	v_add_u32_e32 v252, v250, v233
	v_add_u32_e32 v253, v252, v240
	v_add_u32_e32 v252, v252, v238
	v_add_u32_e32 v251, v250, v241
	v_add_u32_e32 v250, v250, v239
	s_waitcnt vmcnt(3)
	ds_write_b128 v252, v[144:147]
	s_waitcnt vmcnt(2)
	ds_write_b128 v250, v[148:151] offset:18432
	s_waitcnt vmcnt(1)
	ds_write_b128 v253, v[152:155]
	s_waitcnt vmcnt(0)
	ds_write_b128 v251, v[156:159] offset:18432

; #define AT_PVRD(addr) do { AT_RDG(vf[0], vf[1], vf[2], vf[3], addr, 0); AT_RDG(vf[4], vf[5], vf[6], vf[7], addr, 1); } while (0)
; __device__ __forceinline__ void attn_phase(KA a, lds8* lds, int tid, int lane, int wave) {
;     ...
;             bprev = bcur; bcur = bnext;
;         }
;         if (map == 1) { AT_PVRD(vaddr0 + bprev); AT_PVMM(vaddr0 + bprev); }
.LBB0_1318:
	s_and_b64 vcc, exec, s[46:47]
	s_cbranch_vccz .LBB0_1320
	v_add_u32_e32 v168, s18, v232
	v_mfma_f32_32x32x16_bf16 v[48:63], v[96:99], v[88:91], v[48:63]
	v_mfma_f32_32x32x16_bf16 v[32:47], v[100:103], v[88:91], v[32:47]
	v_mfma_f32_32x32x16_bf16 v[16:31], v[104:107], v[88:91], v[16:31]
	v_mfma_f32_32x32x16_bf16 v[0:15], v[108:111], v[88:91], v[0:15]
	ds_read_b128 v[88:91], v168 offset:64
	ds_read_b128 v[96:99], v168 offset:0x1240
	ds_read_b128 v[100:103], v168 offset:0x2440
	ds_read_b128 v[104:107], v168 offset:0x3640
	ds_read_b128 v[108:111], v168 offset:0x60
	ds_read_b128 v[160:163], v168 offset:0x1260
	ds_read_b128 v[164:167], v168 offset:0x2460
	v_mfma_f32_32x32x16_bf16 v[48:63], v[112:115], v[92:95], v[48:63]
	v_mfma_f32_32x32x16_bf16 v[32:47], v[116:119], v[92:95], v[32:47]
	v_mfma_f32_32x32x16_bf16 v[16:31], v[120:123], v[92:95], v[16:31]
	v_mfma_f32_32x32x16_bf16 v[0:15], v[124:127], v[92:95], v[0:15]
	ds_read_b128 v[92:95], v168 offset:0x3660
	s_waitcnt lgkmcnt(0)
	v_mfma_f32_32x32x16_bf16 v[48:63], v[88:91], v[80:83], v[48:63]
	v_mfma_f32_32x32x16_bf16 v[32:47], v[96:99], v[80:83], v[32:47]
	v_mfma_f32_32x32x16_bf16 v[16:31], v[100:103], v[80:83], v[16:31]
	v_mfma_f32_32x32x16_bf16 v[0:15], v[104:107], v[80:83], v[0:15]
	v_mfma_f32_32x32x16_bf16 v[48:63], v[108:111], v[84:87], v[48:63]
	v_mfma_f32_32x32x16_bf16 v[32:47], v[160:163], v[84:87], v[32:47]
	v_mfma_f32_32x32x16_bf16 v[16:31], v[164:167], v[84:87], v[16:31]
	v_mfma_f32_32x32x16_bf16 v[0:15], v[92:95], v[84:87], v[0:15]
	v_xor_b32_e32 v108, 32, v248
	v_lshlrev_b32_e32 v108, 2, v108
